# v6 + MLA unit prologue: query-row loads and q-norm gain loads issued as batches (was one dependent round trip per 16 bytes)
# speedup vs baseline: 1.0049x; 1.0049x over previous
.LBB0_909:
	s_nop 0
	v_readlane_b32 s1, v255, 30
	s_add_i32 s9, s1, s55
	v_readlane_b32 s1, v255, 29
	s_cmp_lt_i32 s55, s1
	v_ashrrev_i32_e32 v177, 5, v176
	s_cselect_b64 s[86:87], -1, 0
	s_cmp_ge_i32 s55, s1
	v_and_b32_e32 v190, 31, v176
	s_cbranch_scc1 .LBB0_911
	v_readlane_b32 s12, v255, 24
	s_mul_i32 s2, s12, 0x600
	v_readlane_b32 s10, v253, 23
	s_mul_hi_u32 s1, s12, 0x600
	v_readlane_b32 s11, v253, 24
	s_add_u32 s2, s10, s2
	s_addc_u32 s1, s11, s1
	s_add_u32 s0, s2, s0
	s_addc_u32 s1, s1, 0
	v_or_b32_e32 v0, s55, v190
	v_mov_b64_e32 v[2:3], s[0:1]
	s_movk_i32 s0, 0x600
	s_waitcnt vmcnt(0)
	v_lshlrev_b32_e32 v34, 3, v177
	v_mad_i64_i32 v[2:3], s[0:1], v0, s0, v[2:3]
	v_ashrrev_i32_e32 v35, 31, v34
	v_lshl_add_u64 v[18:19], v[34:35], 1, v[2:3]
	global_load_dwordx4 v[2:5], v[18:19], off offset:256
	global_load_dwordx4 v[10:13], v[18:19], off offset:288
	global_load_dwordx4 v[6:9], v[18:19], off offset:320
	global_load_dwordx4 v[14:17], v[18:19], off offset:352
	global_load_dwordx4 v[20:23], v[18:19], off
	global_load_dwordx4 v[194:197], v[18:19], off offset:32
	global_load_dwordx4 v[198:201], v[18:19], off offset:64
	global_load_dwordx4 v[202:205], v[18:19], off offset:96
	global_load_dwordx4 v[206:209], v[18:19], off offset:128
	global_load_dwordx4 v[210:213], v[18:19], off offset:160
	global_load_dwordx4 v[214:217], v[18:19], off offset:192
	global_load_dwordx4 v[218:221], v[18:19], off offset:224
	s_add_i32 s0, s12, s55
	s_mov_b32 s2, 0xf800000
	v_readlane_b32 s13, v255, 25
	s_waitcnt vmcnt(10)
	v_lshlrev_b32_e32 v41, 16, v12
	v_and_b32_e32 v39, 0xffff0000, v12
	s_waitcnt vmcnt(8)
	v_lshlrev_b32_e32 v40, 16, v16
	s_waitcnt vmcnt(7)
	v_lshlrev_b32_e32 v109, 16, v20
	v_and_b32_e32 v108, 0xffff0000, v20
	v_lshlrev_b32_e32 v110, 16, v21
	v_and_b32_e32 v111, 0xffff0000, v21
	v_lshlrev_b32_e32 v112, 16, v22
	v_and_b32_e32 v113, 0xffff0000, v22
	v_lshlrev_b32_e32 v114, 16, v23
	v_and_b32_e32 v115, 0xffff0000, v23
	v_mul_f32_e32 v0, v108, v108
	v_fmac_f32_e32 v0, v109, v109
	v_fmac_f32_e32 v0, v110, v110
	v_fmac_f32_e32 v0, v111, v111
	v_fmac_f32_e32 v0, v112, v112
	v_fmac_f32_e32 v0, v113, v113
	v_fmac_f32_e32 v0, v114, v114
	v_fmac_f32_e32 v0, v115, v115
	v_and_b32_e32 v38, 0xffff0000, v16
	v_and_b32_e32 v16, 0xffff0000, v7
	v_lshlrev_b32_e32 v44, 16, v15
	v_and_b32_e32 v42, 0xffff0000, v15
	v_lshlrev_b32_e32 v48, 16, v14
	v_and_b32_e32 v46, 0xffff0000, v14
	v_lshlrev_b32_e32 v15, 16, v4
	v_lshlrev_b32_e32 v14, 16, v8
	v_lshlrev_b32_e32 v49, 16, v10
	v_and_b32_e32 v47, 0xffff0000, v10
	v_lshlrev_b32_e32 v12, 16, v9
	v_and_b32_e32 v10, 0xffff0000, v9
	v_pk_mul_f32 v[136:137], v[14:15], v[14:15]
	v_and_b32_e32 v9, 0xffff0000, v4
	v_and_b32_e32 v8, 0xffff0000, v8
	v_lshlrev_b32_e32 v45, 16, v11
	v_and_b32_e32 v43, 0xffff0000, v11
	v_and_b32_e32 v11, 0xffff0000, v5
	v_pk_mul_f32 v[134:135], v[10:11], v[10:11]
	v_pk_mul_f32 v[128:129], v[48:49], v[48:49]
	v_pk_mul_f32 v[130:131], v[46:47], v[46:47]
	v_pk_mul_f32 v[124:125], v[44:45], v[44:45]
	v_pk_mul_f32 v[126:127], v[42:43], v[42:43]
	v_pk_mul_f32 v[120:121], v[40:41], v[40:41]
	v_pk_mul_f32 v[122:123], v[38:39], v[38:39]
	s_waitcnt vmcnt(6)
	v_lshlrev_b32_e32 v100, 16, v194
	v_and_b32_e32 v101, 0xffff0000, v194
	v_lshlrev_b32_e32 v102, 16, v195
	v_and_b32_e32 v103, 0xffff0000, v195
	v_lshlrev_b32_e32 v104, 16, v196
	v_and_b32_e32 v105, 0xffff0000, v196
	v_lshlrev_b32_e32 v106, 16, v197
	v_and_b32_e32 v107, 0xffff0000, v197
	v_fmac_f32_e32 v0, v100, v100
	v_fmac_f32_e32 v0, v101, v101
	v_fmac_f32_e32 v0, v102, v102
	v_fmac_f32_e32 v0, v103, v103
	v_fmac_f32_e32 v0, v104, v104
	v_fmac_f32_e32 v0, v105, v105
	v_fmac_f32_e32 v0, v106, v106
	v_fmac_f32_e32 v0, v107, v107
	s_waitcnt vmcnt(5)
	v_lshlrev_b32_e32 v92, 16, v198
	v_and_b32_e32 v93, 0xffff0000, v198
	v_lshlrev_b32_e32 v94, 16, v199
	v_and_b32_e32 v95, 0xffff0000, v199
	v_lshlrev_b32_e32 v96, 16, v200
	v_and_b32_e32 v97, 0xffff0000, v200
	v_lshlrev_b32_e32 v98, 16, v201
	v_and_b32_e32 v99, 0xffff0000, v201
	v_fmac_f32_e32 v0, v92, v92
	v_fmac_f32_e32 v0, v93, v93
	v_fmac_f32_e32 v0, v94, v94
	v_fmac_f32_e32 v0, v95, v95
	v_fmac_f32_e32 v0, v96, v96
	v_fmac_f32_e32 v0, v97, v97
	v_fmac_f32_e32 v0, v98, v98
	v_fmac_f32_e32 v0, v99, v99
	s_waitcnt vmcnt(4)
	v_lshlrev_b32_e32 v84, 16, v202
	v_and_b32_e32 v85, 0xffff0000, v202
	v_lshlrev_b32_e32 v86, 16, v203
	v_and_b32_e32 v87, 0xffff0000, v203
	v_lshlrev_b32_e32 v88, 16, v204
	v_and_b32_e32 v89, 0xffff0000, v204
	v_lshlrev_b32_e32 v90, 16, v205
	v_and_b32_e32 v91, 0xffff0000, v205
	v_fmac_f32_e32 v0, v84, v84
	v_fmac_f32_e32 v0, v85, v85
	v_fmac_f32_e32 v0, v86, v86
	v_fmac_f32_e32 v0, v87, v87
	v_fmac_f32_e32 v0, v88, v88
	v_fmac_f32_e32 v0, v89, v89
	v_fmac_f32_e32 v0, v90, v90
	v_fmac_f32_e32 v0, v91, v91
	s_waitcnt vmcnt(3)
	v_lshlrev_b32_e32 v76, 16, v206
	v_and_b32_e32 v77, 0xffff0000, v206
	v_lshlrev_b32_e32 v78, 16, v207
	v_and_b32_e32 v79, 0xffff0000, v207
	v_lshlrev_b32_e32 v80, 16, v208
	v_and_b32_e32 v81, 0xffff0000, v208
	v_lshlrev_b32_e32 v82, 16, v209
	v_and_b32_e32 v83, 0xffff0000, v209
	v_fmac_f32_e32 v0, v76, v76
	v_fmac_f32_e32 v0, v77, v77
	v_fmac_f32_e32 v0, v78, v78
	v_fmac_f32_e32 v0, v79, v79
	v_fmac_f32_e32 v0, v80, v80
	v_fmac_f32_e32 v0, v81, v81
	v_fmac_f32_e32 v0, v82, v82
	v_fmac_f32_e32 v0, v83, v83
	s_waitcnt vmcnt(2)
	v_lshlrev_b32_e32 v68, 16, v210
	v_and_b32_e32 v69, 0xffff0000, v210
	v_lshlrev_b32_e32 v70, 16, v211
	v_and_b32_e32 v71, 0xffff0000, v211
	v_lshlrev_b32_e32 v72, 16, v212
	v_and_b32_e32 v73, 0xffff0000, v212
	v_lshlrev_b32_e32 v74, 16, v213
	v_and_b32_e32 v75, 0xffff0000, v213
	v_fmac_f32_e32 v0, v68, v68
	v_fmac_f32_e32 v0, v69, v69
	v_fmac_f32_e32 v0, v70, v70
	v_fmac_f32_e32 v0, v71, v71
	v_fmac_f32_e32 v0, v72, v72
	v_fmac_f32_e32 v0, v73, v73
	v_fmac_f32_e32 v0, v74, v74
	v_fmac_f32_e32 v0, v75, v75
	s_waitcnt vmcnt(1)
	v_lshlrev_b32_e32 v60, 16, v214
	v_and_b32_e32 v61, 0xffff0000, v214
	v_lshlrev_b32_e32 v62, 16, v215
	v_and_b32_e32 v63, 0xffff0000, v215
	v_lshlrev_b32_e32 v64, 16, v216
	v_and_b32_e32 v65, 0xffff0000, v216
	v_lshlrev_b32_e32 v66, 16, v217
	v_and_b32_e32 v67, 0xffff0000, v217
	v_fmac_f32_e32 v0, v60, v60
	v_fmac_f32_e32 v0, v61, v61
	v_fmac_f32_e32 v0, v62, v62
	v_fmac_f32_e32 v0, v63, v63
	v_fmac_f32_e32 v0, v64, v64
	v_fmac_f32_e32 v0, v65, v65
	v_fmac_f32_e32 v0, v66, v66
	v_fmac_f32_e32 v0, v67, v67
	s_waitcnt vmcnt(0)
	v_lshlrev_b32_e32 v52, 16, v218
	v_and_b32_e32 v53, 0xffff0000, v218
	v_add_u32_e32 v18, s0, v190
	v_lshlrev_b32_e32 v54, 16, v219
	v_and_b32_e32 v55, 0xffff0000, v219
	v_ashrrev_i32_e32 v19, 31, v18
	v_readlane_b32 s0, v251, 47
	v_lshlrev_b64 v[18:19], 6, v[18:19]
	v_readlane_b32 s1, v251, 48
	v_lshlrev_b32_e32 v56, 16, v220
	v_and_b32_e32 v57, 0xffff0000, v220
	v_lshl_add_u64 v[30:31], s[0:1], 0, v[18:19]
	v_lshlrev_b32_e32 v58, 16, v221
	v_and_b32_e32 v59, 0xffff0000, v221
	global_load_dwordx4 v[18:21], v[30:31], off offset:48
	global_load_dwordx4 v[22:25], v[30:31], off offset:32
	global_load_dwordx4 v[26:29], v[30:31], off offset:16
	s_nop 0
	global_load_dwordx4 v[30:33], v[30:31], off
	v_fmac_f32_e32 v0, v52, v52
	v_fmac_f32_e32 v0, v53, v53
	v_fmac_f32_e32 v0, v54, v54
	v_fmac_f32_e32 v0, v55, v55
	v_fmac_f32_e32 v0, v56, v56
	v_fmac_f32_e32 v0, v57, v57
	v_fmac_f32_e32 v0, v58, v58
	v_fmac_f32_e32 v0, v59, v59
	s_waitcnt vmcnt(2)
	v_add_f32_e32 v22, v22, v23
	v_add_f32_e32 v24, v24, v25
	s_waitcnt vmcnt(0)
	v_mov_b32_e32 v36, v31
	v_mov_b32_e32 v37, v32
	v_mov_b32_e32 v31, v33
	v_mov_b32_e32 v32, v27
	v_mov_b32_e32 v33, v28
	v_mov_b32_e32 v27, v29
	v_pk_add_f32 v[30:31], v[36:37], v[30:31]
	v_pk_add_f32 v[26:27], v[32:33], v[26:27]
	v_add_f32_e32 v30, v30, v31
	v_pk_add_f32 v[26:27], v[26:27], v[26:27] op_sel:[0,1] op_sel_hi:[1,0]
	v_add_f32_e32 v30, 0, v30
	v_mov_b32_e32 v31, v18
	v_mov_b32_e32 v27, v19
	v_mov_b32_e32 v23, v20
	v_mov_b32_e32 v25, v21
	v_pk_add_f32 v[18:19], v[30:31], v[26:27]
	v_pk_add_f32 v[20:21], v[22:23], v[24:25]
	v_lshlrev_b32_e32 v36, 16, v17
	v_pk_add_f32 v[18:19], v[18:19], v[20:21]
	v_lshlrev_b32_e32 v37, 16, v13
	v_add_f32_e32 v18, v18, v19
	v_fmamk_f32 v18, v18, 0x3b000000, v230
	v_cmp_gt_f32_e32 vcc, s2, v18
	v_mul_f32_e32 v19, 0x4f800000, v18
	v_pk_mul_f32 v[28:29], v[36:37], v[36:37]
	v_cndmask_b32_e32 v18, v18, v19, vcc
	v_sqrt_f32_e32 v19, v18
	s_nop 0
	v_add_u32_e32 v20, -1, v19
	v_fma_f32 v21, -v20, v19, v18
	v_cmp_ge_f32_e64 s[0:1], 0, v21
	v_add_u32_e32 v21, 1, v19
	s_nop 0
	v_cndmask_b32_e64 v20, v19, v20, s[0:1]
	v_fma_f32 v19, -v21, v19, v18
	v_cmp_lt_f32_e64 s[0:1], 0, v19
	s_nop 1
	v_cndmask_b32_e64 v19, v20, v21, s[0:1]
	v_mul_f32_e32 v20, 0x37800000, v19
	v_cndmask_b32_e32 v19, v19, v20, vcc
	v_cmp_class_f32_e32 vcc, v18, v228
	s_nop 1
	v_cndmask_b32_e32 v18, v19, v18, vcc
	v_div_scale_f32 v19, s[0:1], v18, v18, 1.0
	v_rcp_f32_e32 v20, v19
	v_readlane_b32 s0, v254, 55
	v_readlane_b32 s1, v254, 56
	v_fma_f32 v21, -v19, v20, 1.0
	v_fmac_f32_e32 v20, v21, v20
	v_div_scale_f32 v21, vcc, 1.0, v18, 1.0
	v_mul_f32_e32 v22, v21, v20
	v_fma_f32 v23, -v19, v22, v21
	v_fmac_f32_e32 v22, v23, v20
	v_fma_f32 v19, -v19, v22, v21
	v_div_fmas_f32 v19, v19, v20, v22
	v_div_fixup_f32 v144, v19, v18, 1.0
	v_add_u32_e32 v18, s9, v190
	v_ashrrev_i32_e32 v19, 31, v18
	v_lshlrev_b64 v[20:21], 8, v[18:19]
	v_lshl_add_u64 v[18:19], v[34:35], 2, s[0:1]
	global_load_dwordx4 v[24:27], v[18:19], off offset:16
	global_load_dwordx4 v[116:119], v[18:19], off
	global_load_dwordx4 v[194:197], v[18:19], off offset:80
	global_load_dwordx4 v[198:201], v[18:19], off offset:64
	global_load_dwordx4 v[202:205], v[18:19], off offset:144
	global_load_dwordx4 v[206:209], v[18:19], off offset:128
	global_load_dwordx4 v[210:213], v[18:19], off offset:208
	global_load_dwordx4 v[214:217], v[18:19], off offset:192
	global_load_dwordx4 v[218:221], v[18:19], off offset:272
	global_load_dwordx4 v[222:225], v[18:19], off offset:256
	global_load_dwordx4 v[234:237], v[18:19], off offset:336
	global_load_dwordx4 v[238:241], v[18:19], off offset:320
	global_load_dwordx4 v[242:245], v[18:19], off offset:400
	global_load_dwordx4 v[246:249], v[18:19], off offset:384
	v_readlane_b32 s0, v253, 29
	v_readlane_b32 s1, v253, 30
	v_lshlrev_b32_e32 v23, 16, v2
	v_lshlrev_b32_e32 v22, 16, v6
	v_lshl_add_u64 v[20:21], s[0:1], 0, v[20:21]
	v_lshl_add_u64 v[30:31], v[34:35], 3, v[20:21]
	v_lshlrev_b32_e32 v20, 16, v7
	v_pk_mul_f32 v[142:143], v[22:23], v[22:23]
	v_and_b32_e32 v7, 0xffff0000, v2
	v_and_b32_e32 v6, 0xffff0000, v6
	v_and_b32_e32 v34, 0xffff0000, v17
	v_lshlrev_b32_e32 v21, 16, v3
	v_and_b32_e32 v17, 0xffff0000, v3
	v_add_f32_e32 v0, v143, v0
	v_pk_mul_f32 v[2:3], v[6:7], v[6:7]
	v_pk_mul_f32 v[138:139], v[20:21], v[20:21]
	v_add_f32_e32 v0, v3, v0
	v_pk_mul_f32 v[140:141], v[16:17], v[16:17]
	v_add_f32_e32 v0, v139, v0
	v_add_f32_e32 v0, v141, v0
	v_and_b32_e32 v35, 0xffff0000, v13
	v_lshlrev_b32_e32 v13, 16, v5
	v_pk_mul_f32 v[4:5], v[8:9], v[8:9]
	v_add_f32_e32 v0, v137, v0
	v_pk_mul_f32 v[132:133], v[12:13], v[12:13]
	v_add_f32_e32 v0, v5, v0
	v_add_f32_e32 v0, v133, v0
	v_add_f32_e32 v0, v135, v0
	v_add_f32_e32 v0, v129, v0
	v_add_f32_e32 v0, v131, v0
	v_add_f32_e32 v0, v125, v0
	v_add_f32_e32 v0, v127, v0
	v_add_f32_e32 v0, v121, v0
	v_add_f32_e32 v0, v123, v0
	v_pk_mul_f32 v[32:33], v[34:35], v[34:35]
	v_add_f32_e32 v0, v29, v0
	v_add_f32_e32 v0, v33, v0
	v_add_f32_e32 v0, v142, v0
	v_add_f32_e32 v0, v2, v0
	v_add_f32_e32 v0, v138, v0
	v_add_f32_e32 v0, v140, v0
	v_add_f32_e32 v0, v136, v0
	v_add_f32_e32 v0, v4, v0
	v_add_f32_e32 v0, v132, v0
	v_add_f32_e32 v0, v134, v0
	v_add_f32_e32 v0, v128, v0
	v_add_f32_e32 v0, v130, v0
	v_add_f32_e32 v0, v124, v0
	v_add_f32_e32 v0, v126, v0
	v_add_f32_e32 v0, v120, v0
	v_add_f32_e32 v0, v122, v0
	v_add_f32_e32 v0, v28, v0
	v_add_f32_e32 v0, v32, v0
	v_mov_b32_e32 v2, v0
	s_nop 1
	v_permlane32_swap_b32_e32 v0, v2
	v_add_f32_e32 v0, v0, v2
	v_mul_f32_e32 v0, v0, v144
	v_mul_f32_e32 v0, v144, v0
	v_fmamk_f32 v0, v0, 0x3baaaaab, v230
	v_cmp_gt_f32_e32 vcc, s2, v0
	v_mul_f32_e32 v2, 0x4f800000, v0
	s_nop 0
	v_cndmask_b32_e32 v0, v0, v2, vcc
	v_sqrt_f32_e32 v2, v0
	s_nop 0
	v_add_u32_e32 v3, -1, v2
	v_fma_f32 v4, -v3, v2, v0
	v_cmp_ge_f32_e64 s[0:1], 0, v4
	v_add_u32_e32 v4, 1, v2
	s_nop 0
	v_cndmask_b32_e64 v3, v2, v3, s[0:1]
	v_fma_f32 v2, -v4, v2, v0
	v_cmp_lt_f32_e64 s[0:1], 0, v2
	s_nop 1
	v_cndmask_b32_e64 v2, v3, v4, s[0:1]
	v_mul_f32_e32 v3, 0x37800000, v2
	v_cndmask_b32_e32 v2, v2, v3, vcc
	v_cmp_class_f32_e32 vcc, v0, v228
	s_nop 1
	v_cndmask_b32_e32 v0, v2, v0, vcc
	v_div_scale_f32 v2, s[0:1], v0, v0, v144
	v_rcp_f32_e32 v3, v2
	s_nop 0
	v_fma_f32 v4, -v2, v3, 1.0
	v_fmac_f32_e32 v3, v4, v3
	v_div_scale_f32 v4, vcc, v144, v0, v144
	v_mul_f32_e32 v5, v4, v3
	v_fma_f32 v28, -v2, v5, v4
	v_fmac_f32_e32 v5, v28, v3
	v_fma_f32 v2, -v2, v5, v4
	v_div_fmas_f32 v2, v2, v3, v5
	v_div_fixup_f32 v0, v2, v0, v144
	v_mul_f32_e32 v0, 0x3dd53b94, v0
	v_mul_f32_e32 v28, v0, v112
	s_waitcnt vmcnt(13)
	v_mul_f32_e32 v24, v24, v28
	v_mul_f32_e32 v28, v0, v113
	v_mul_f32_e32 v25, v25, v28
	v_mul_f32_e32 v28, v0, v114
	v_mul_f32_e32 v2, v0, v109
	v_mul_f32_e32 v3, v0, v108
	v_mul_f32_e32 v4, v0, v110
	v_mul_f32_e32 v5, v0, v111
	v_mul_f32_e32 v26, v26, v28
	v_mul_f32_e32 v28, v0, v115
	s_waitcnt vmcnt(12)
	v_mul_f32_e32 v2, v116, v2
	v_mul_f32_e32 v3, v117, v3
	v_mul_f32_e32 v4, v118, v4
	v_mul_f32_e32 v5, v119, v5
	v_mul_f32_e32 v27, v27, v28
	v_cvt_pk_bf16_f32 v128, v2, v3
	v_cvt_pk_bf16_f32 v129, v4, v5
	v_cvt_pk_bf16_f32 v130, v24, v25
	v_cvt_pk_bf16_f32 v131, v26, v27
	v_mul_f32_e32 v28, v0, v100
	v_pk_mul_f32 v[22:23], v[0:1], v[22:23] op_sel_hi:[0,1]
	v_pk_mul_f32 v[6:7], v[0:1], v[6:7] op_sel_hi:[0,1]
	v_pk_mul_f32 v[48:49], v[0:1], v[48:49] op_sel_hi:[0,1]
	s_waitcnt vmcnt(10)
	v_mul_f32_e32 v24, v198, v28
	v_mul_f32_e32 v28, v0, v101
	v_mul_f32_e32 v25, v199, v28
	v_mul_f32_e32 v28, v0, v102
	v_mul_f32_e32 v26, v200, v28
	v_mul_f32_e32 v28, v0, v103
	v_mul_f32_e32 v27, v201, v28
	v_mul_f32_e32 v28, v0, v104
	v_mul_f32_e32 v2, v194, v28
	v_mul_f32_e32 v28, v0, v105
	v_mul_f32_e32 v3, v195, v28
	v_mul_f32_e32 v28, v0, v106
	v_mul_f32_e32 v4, v196, v28
	v_mul_f32_e32 v28, v0, v107
	v_mul_f32_e32 v5, v197, v28
	v_cvt_pk_bf16_f32 v132, v24, v25
	v_cvt_pk_bf16_f32 v133, v26, v27
	v_cvt_pk_bf16_f32 v134, v2, v3
	v_cvt_pk_bf16_f32 v135, v4, v5
	v_mul_f32_e32 v28, v0, v92
	s_waitcnt vmcnt(8)
	v_mul_f32_e32 v24, v206, v28
	v_mul_f32_e32 v28, v0, v93
	v_mul_f32_e32 v25, v207, v28
	v_mul_f32_e32 v28, v0, v94
	v_mul_f32_e32 v26, v208, v28
	v_mul_f32_e32 v28, v0, v95
	v_mul_f32_e32 v27, v209, v28
	v_mul_f32_e32 v28, v0, v96
	v_mul_f32_e32 v2, v202, v28
	v_mul_f32_e32 v28, v0, v97
	v_mul_f32_e32 v3, v203, v28
	v_mul_f32_e32 v28, v0, v98
	v_mul_f32_e32 v4, v204, v28
	v_mul_f32_e32 v28, v0, v99
	v_mul_f32_e32 v5, v205, v28
	v_cvt_pk_bf16_f32 v136, v24, v25
	v_cvt_pk_bf16_f32 v137, v26, v27
	v_cvt_pk_bf16_f32 v138, v2, v3
	v_cvt_pk_bf16_f32 v139, v4, v5
	v_mul_f32_e32 v28, v0, v84
	s_waitcnt vmcnt(6)
	v_mul_f32_e32 v24, v28, v214
	v_mul_f32_e32 v28, v0, v85
	v_mul_f32_e32 v25, v28, v215
	v_mul_f32_e32 v28, v0, v86
	v_mul_f32_e32 v26, v28, v216
	v_mul_f32_e32 v28, v0, v87
	v_mul_f32_e32 v27, v28, v217
	v_mul_f32_e32 v28, v0, v88
	v_mul_f32_e32 v2, v28, v210
	v_mul_f32_e32 v28, v0, v89
	v_mul_f32_e32 v3, v28, v211
	v_mul_f32_e32 v28, v0, v90
	v_mul_f32_e32 v4, v28, v212
	v_mul_f32_e32 v28, v0, v91
	v_mul_f32_e32 v5, v28, v213
	v_cvt_pk_bf16_f32 v140, v24, v25
	v_cvt_pk_bf16_f32 v141, v26, v27
	v_cvt_pk_bf16_f32 v142, v2, v3
	v_cvt_pk_bf16_f32 v143, v4, v5
	v_mul_f32_e32 v28, v0, v76
	s_waitcnt vmcnt(4)
	v_mul_f32_e32 v24, v28, v222
	v_mul_f32_e32 v28, v0, v77
	v_mul_f32_e32 v25, v28, v223
	v_mul_f32_e32 v28, v0, v78
	v_mul_f32_e32 v26, v28, v224
	v_mul_f32_e32 v28, v0, v79
	v_mul_f32_e32 v27, v28, v225
	v_mul_f32_e32 v28, v0, v80
	v_mul_f32_e32 v2, v28, v218
	v_mul_f32_e32 v28, v0, v81
	v_mul_f32_e32 v3, v28, v219
	v_mul_f32_e32 v28, v0, v82
	v_mul_f32_e32 v4, v28, v220
	v_mul_f32_e32 v28, v0, v83
	v_mul_f32_e32 v5, v28, v221
	v_cvt_pk_bf16_f32 v144, v24, v25
	v_cvt_pk_bf16_f32 v145, v26, v27
	v_cvt_pk_bf16_f32 v146, v2, v3
	v_cvt_pk_bf16_f32 v147, v4, v5
	v_mul_f32_e32 v28, v0, v68
	s_waitcnt vmcnt(2)
	v_mul_f32_e32 v24, v28, v238
	v_mul_f32_e32 v28, v0, v69
	v_mul_f32_e32 v25, v28, v239
	v_mul_f32_e32 v28, v0, v70
	v_mul_f32_e32 v26, v28, v240
	v_mul_f32_e32 v28, v0, v71
	v_mul_f32_e32 v27, v28, v241
	v_mul_f32_e32 v28, v0, v72
	v_mul_f32_e32 v2, v28, v234
	v_mul_f32_e32 v28, v0, v73
	v_mul_f32_e32 v3, v28, v235
	v_mul_f32_e32 v28, v0, v74
	v_mul_f32_e32 v4, v28, v236
	v_mul_f32_e32 v28, v0, v75
	v_mul_f32_e32 v5, v28, v237
	v_cvt_pk_bf16_f32 v148, v24, v25
	v_cvt_pk_bf16_f32 v149, v26, v27
	v_cvt_pk_bf16_f32 v150, v2, v3
	v_cvt_pk_bf16_f32 v151, v4, v5
	v_mul_f32_e32 v28, v0, v60
	s_waitcnt vmcnt(0)
	v_mul_f32_e32 v24, v28, v246
	v_mul_f32_e32 v28, v0, v61
	v_mul_f32_e32 v25, v28, v247
	v_mul_f32_e32 v28, v0, v62
	v_mul_f32_e32 v26, v28, v248
	v_mul_f32_e32 v28, v0, v63
	v_mul_f32_e32 v27, v28, v249
	v_mul_f32_e32 v28, v0, v64
	v_mul_f32_e32 v2, v28, v242
	v_mul_f32_e32 v28, v0, v65
	v_mul_f32_e32 v3, v28, v243
	v_mul_f32_e32 v28, v0, v66
	v_mul_f32_e32 v4, v28, v244
	v_mul_f32_e32 v28, v0, v67
	v_mul_f32_e32 v5, v28, v245
	v_cvt_pk_bf16_f32 v152, v24, v25
	v_cvt_pk_bf16_f32 v153, v26, v27
	v_cvt_pk_bf16_f32 v154, v2, v3
	v_cvt_pk_bf16_f32 v155, v4, v5
	global_load_dwordx4 v[2:5], v[18:19], off offset:464
	global_load_dwordx4 v[24:27], v[18:19], off offset:448
	v_mul_f32_e32 v28, v0, v52
	s_waitcnt vmcnt(0)
	v_mul_f32_e32 v24, v28, v24
	v_mul_f32_e32 v28, v0, v53
	v_mul_f32_e32 v25, v28, v25
	v_mul_f32_e32 v28, v0, v54
	v_mul_f32_e32 v26, v28, v26
	v_mul_f32_e32 v28, v0, v55
	v_mul_f32_e32 v27, v28, v27
	v_mul_f32_e32 v28, v0, v56
	v_mul_f32_e32 v2, v28, v2
	v_mul_f32_e32 v28, v0, v57
	v_mul_f32_e32 v3, v28, v3
	v_mul_f32_e32 v28, v0, v58
	v_mul_f32_e32 v4, v28, v4
	v_mul_f32_e32 v28, v0, v59
	v_mul_f32_e32 v5, v28, v5
	v_cvt_pk_bf16_f32 v156, v24, v25
	v_cvt_pk_bf16_f32 v157, v26, v27
	v_cvt_pk_bf16_f32 v158, v2, v3
	v_cvt_pk_bf16_f32 v159, v4, v5
	global_load_dwordx4 v[2:5], v[18:19], off offset:528
	global_load_dwordx4 v[24:27], v[18:19], off offset:512
	global_load_dwordx4 v[52:55], v[18:19], off offset:656
	global_load_dwordx4 v[56:59], v[18:19], off offset:640
	global_load_dwordx4 v[60:63], v[30:31], off offset:48
	global_load_dwordx4 v[64:67], v[30:31], off offset:32
	global_load_dwordx4 v[68:71], v[30:31], off offset:16
	global_load_dwordx4 v[72:75], v[30:31], off
	s_waitcnt vmcnt(6)
	v_mov_b32_e32 v29, v24
	s_waitcnt vmcnt(4)
	v_mov_b32_e32 v28, v56
	v_pk_mul_f32 v[22:23], v[22:23], v[28:29]
	v_mov_b32_e32 v24, v57
	v_pk_mul_f32 v[6:7], v[6:7], v[24:25]
	s_waitcnt vmcnt(0)
	v_pk_mul_f32 v[28:29], v[22:23], v[72:73] op_sel:[1,0] op_sel_hi:[0,1]
	v_pk_mul_f32 v[22:23], v[22:23], v[72:73]
	v_sub_f32_e32 v28, v28, v29
	v_add_f32_e32 v29, v23, v22
	v_pk_mul_f32 v[22:23], v[6:7], v[74:75] op_sel:[1,0] op_sel_hi:[0,1]
	v_pk_mul_f32 v[6:7], v[6:7], v[74:75]
	v_sub_f32_e32 v22, v22, v23
	v_add_f32_e32 v23, v7, v6
	v_pk_mul_f32 v[6:7], v[0:1], v[20:21] op_sel_hi:[0,1]
	v_mov_b32_e32 v20, v58
	v_mov_b32_e32 v21, v26
	v_pk_mul_f32 v[6:7], v[6:7], v[20:21]
	v_mov_b32_e32 v26, v59
	v_pk_mul_f32 v[20:21], v[6:7], v[68:69] op_sel:[1,0] op_sel_hi:[0,1]
	v_pk_mul_f32 v[6:7], v[6:7], v[68:69]
	v_sub_f32_e32 v20, v20, v21
	v_add_f32_e32 v21, v7, v6
	v_pk_mul_f32 v[6:7], v[0:1], v[16:17] op_sel_hi:[0,1]
	v_pk_mul_f32 v[6:7], v[6:7], v[26:27]
	v_cvt_pk_bf16_f32 v160, v28, v22
	v_cvt_pk_bf16_f32 v164, v29, v23
	s_nop 0
	v_pk_mul_f32 v[16:17], v[6:7], v[70:71] op_sel:[1,0] op_sel_hi:[0,1]
	v_pk_mul_f32 v[6:7], v[6:7], v[70:71]
	v_sub_f32_e32 v16, v16, v17
	v_add_f32_e32 v17, v7, v6
	v_pk_mul_f32 v[6:7], v[0:1], v[14:15] op_sel_hi:[0,1]
	v_mov_b32_e32 v14, v52
	v_mov_b32_e32 v15, v2
	v_pk_mul_f32 v[6:7], v[6:7], v[14:15]
	v_mov_b32_e32 v2, v53
	v_pk_mul_f32 v[14:15], v[6:7], v[64:65] op_sel:[1,0] op_sel_hi:[0,1]
	v_pk_mul_f32 v[6:7], v[6:7], v[64:65]
	v_sub_f32_e32 v14, v14, v15
	v_add_f32_e32 v15, v7, v6
	v_pk_mul_f32 v[6:7], v[0:1], v[8:9] op_sel_hi:[0,1]
	v_pk_mul_f32 v[2:3], v[6:7], v[2:3]
	v_cvt_pk_bf16_f32 v161, v20, v16
	v_cvt_pk_bf16_f32 v165, v21, v17
	s_nop 0
	v_pk_mul_f32 v[6:7], v[2:3], v[66:67] op_sel:[1,0] op_sel_hi:[0,1]
	v_pk_mul_f32 v[2:3], v[2:3], v[66:67]
	v_sub_f32_e32 v8, v6, v7
	v_add_f32_e32 v9, v3, v2
	v_pk_mul_f32 v[2:3], v[0:1], v[12:13] op_sel_hi:[0,1]
	v_mov_b32_e32 v6, v54
	v_mov_b32_e32 v7, v4
	v_pk_mul_f32 v[2:3], v[2:3], v[6:7]
	v_mov_b32_e32 v4, v55
	v_pk_mul_f32 v[6:7], v[2:3], v[60:61] op_sel:[1,0] op_sel_hi:[0,1]
	v_pk_mul_f32 v[2:3], v[2:3], v[60:61]
	v_sub_f32_e32 v6, v6, v7
	v_add_f32_e32 v7, v3, v2
	v_pk_mul_f32 v[2:3], v[0:1], v[10:11] op_sel_hi:[0,1]
	v_pk_mul_f32 v[2:3], v[2:3], v[4:5]
	v_cvt_pk_bf16_f32 v162, v14, v8
	v_cvt_pk_bf16_f32 v166, v15, v9
	s_nop 0
	v_pk_mul_f32 v[4:5], v[2:3], v[62:63] op_sel:[1,0] op_sel_hi:[0,1]
	v_pk_mul_f32 v[2:3], v[2:3], v[62:63]
	v_sub_f32_e32 v4, v4, v5
	v_add_f32_e32 v2, v3, v2
	v_cvt_pk_bf16_f32 v163, v6, v4
	v_cvt_pk_bf16_f32 v167, v7, v2
	global_load_dwordx4 v[2:5], v[18:19], off offset:592
	global_load_dwordx4 v[6:9], v[18:19], off offset:576
	global_load_dwordx4 v[10:13], v[18:19], off offset:720
	global_load_dwordx4 v[22:25], v[18:19], off offset:704
	global_load_dwordx4 v[14:17], v[30:31], off offset:176
	s_nop 0
	global_load_dwordx4 v[18:21], v[30:31], off offset:160
	global_load_dwordx4 v[26:29], v[30:31], off offset:144
	s_nop 0
	global_load_dwordx4 v[30:33], v[30:31], off offset:128
	s_waitcnt vmcnt(6)
	v_mov_b32_e32 v53, v6
	s_waitcnt vmcnt(4)
	v_mov_b32_e32 v52, v22
	v_pk_mul_f32 v[48:49], v[48:49], v[52:53]
	v_mov_b32_e32 v6, v23
	s_waitcnt vmcnt(0)
	v_pk_mul_f32 v[52:53], v[48:49], v[30:31] op_sel:[1,0] op_sel_hi:[0,1]
	v_pk_mul_f32 v[30:31], v[48:49], v[30:31]
	v_sub_f32_e32 v52, v52, v53
	v_add_f32_e32 v48, v31, v30
	v_pk_mul_f32 v[30:31], v[0:1], v[46:47] op_sel_hi:[0,1]
	v_pk_mul_f32 v[6:7], v[30:31], v[6:7]
	s_nop 0
	v_pk_mul_f32 v[22:23], v[6:7], v[32:33] op_sel:[1,0] op_sel_hi:[0,1]
	v_pk_mul_f32 v[6:7], v[6:7], v[32:33]
	v_sub_f32_e32 v30, v22, v23
	v_add_f32_e32 v31, v7, v6
	v_pk_mul_f32 v[6:7], v[0:1], v[44:45] op_sel_hi:[0,1]
	v_mov_b32_e32 v22, v24
	v_mov_b32_e32 v23, v8
	v_pk_mul_f32 v[6:7], v[6:7], v[22:23]
	v_mov_b32_e32 v8, v25
	v_pk_mul_f32 v[22:23], v[6:7], v[26:27] op_sel:[1,0] op_sel_hi:[0,1]
	v_pk_mul_f32 v[6:7], v[6:7], v[26:27]
	v_sub_f32_e32 v22, v22, v23
	v_add_f32_e32 v23, v7, v6
	v_pk_mul_f32 v[6:7], v[0:1], v[42:43] op_sel_hi:[0,1]
	v_pk_mul_f32 v[6:7], v[6:7], v[8:9]
	v_cvt_pk_bf16_f32 v168, v52, v30
	v_cvt_pk_bf16_f32 v172, v48, v31
	s_nop 0
	v_pk_mul_f32 v[8:9], v[6:7], v[28:29] op_sel:[1,0] op_sel_hi:[0,1]
	v_pk_mul_f32 v[6:7], v[6:7], v[28:29]
	v_sub_f32_e32 v24, v8, v9
	v_add_f32_e32 v25, v7, v6
	v_pk_mul_f32 v[6:7], v[0:1], v[40:41] op_sel_hi:[0,1]
	v_mov_b32_e32 v8, v10
	v_mov_b32_e32 v9, v2
	v_pk_mul_f32 v[6:7], v[6:7], v[8:9]
	v_mov_b32_e32 v2, v11
	v_pk_mul_f32 v[8:9], v[6:7], v[18:19] op_sel:[1,0] op_sel_hi:[0,1]
	v_pk_mul_f32 v[6:7], v[6:7], v[18:19]
	v_sub_f32_e32 v8, v8, v9
	v_add_f32_e32 v9, v7, v6
	v_pk_mul_f32 v[6:7], v[0:1], v[38:39] op_sel_hi:[0,1]
	v_pk_mul_f32 v[2:3], v[6:7], v[2:3]
	v_cvt_pk_bf16_f32 v169, v22, v24
	v_cvt_pk_bf16_f32 v173, v23, v25
	s_nop 0
	v_pk_mul_f32 v[6:7], v[2:3], v[20:21] op_sel:[1,0] op_sel_hi:[0,1]
	v_pk_mul_f32 v[2:3], v[2:3], v[20:21]
	v_sub_f32_e32 v10, v6, v7
	v_add_f32_e32 v11, v3, v2
	v_pk_mul_f32 v[2:3], v[0:1], v[36:37] op_sel_hi:[0,1]
	v_mov_b32_e32 v6, v12
	v_mov_b32_e32 v7, v4
	v_pk_mul_f32 v[2:3], v[2:3], v[6:7]
	v_mov_b32_e32 v4, v13
	v_pk_mul_f32 v[6:7], v[2:3], v[14:15] op_sel:[1,0] op_sel_hi:[0,1]
	v_pk_mul_f32 v[2:3], v[2:3], v[14:15]
	v_sub_f32_e32 v6, v6, v7
	v_add_f32_e32 v7, v3, v2
	v_pk_mul_f32 v[2:3], v[0:1], v[34:35] op_sel_hi:[0,1]
	v_pk_mul_f32 v[2:3], v[2:3], v[4:5]
	v_cvt_pk_bf16_f32 v170, v8, v10
	v_cvt_pk_bf16_f32 v174, v9, v11
	s_nop 0
	v_pk_mul_f32 v[4:5], v[2:3], v[16:17] op_sel:[1,0] op_sel_hi:[0,1]
	v_pk_mul_f32 v[2:3], v[2:3], v[16:17]
	v_sub_f32_e32 v0, v4, v5
	v_add_f32_e32 v2, v3, v2
	v_cvt_pk_bf16_f32 v171, v6, v0
	v_cvt_pk_bf16_f32 v175, v7, v2
	s_branch .LBB0_912
